# v037 + cross-attention K/V fragment LDS reads batched (16 in flight) instead of read-wait-MFMA one at a time, loop and peeled last step
# speedup vs baseline: 1.0008x; 1.0008x over previous
; #define LAS __attribute__((address_space(3)))
; template <int HD, int MODE> ...
;     ...
;             if constexpr (HD == 64) {
;                 bf16x8 vfr[HD / 32][4];
; #pragma unroll
;                 for (int d0 = 0; d0 < HD / 32; ++d0)
; #pragma unroll
;                     for (int kk = 0; kk < 4; ++kk) vfr[d0][kk] = *(const LAS bf16x8*)(vb + d0 * 32 * VROW + kk * 32);
;                 __builtin_amdgcn_sched_barrier(0);
;                 __builtin_amdgcn_s_setprio(1);
; #pragma unroll
;                 for (int d0 = 0; d0 < HD / 32; ++d0)
; #pragma unroll
;                     for (int kk = 0; kk < 4; ++kk) o[d0] = __builtin_amdgcn_mfma_f32_32x32x16_bf16(vfr[d0][kk], pf[kk], o[d0], 0, 0, 0);
;                 __builtin_amdgcn_s_setprio(0);
;             } else {
;             __builtin_amdgcn_s_setprio(1);
; #pragma unroll
;             for (int d0 = 0; d0 < HD / 32; ++d0)
; #pragma unroll
;                 for (int kk = 0; kk < 4; ++kk) {
;                     const bf16x8 vf = *(const LAS bf16x8*)(vb + d0 * 32 * VROW + kk * 32);
;                     o[d0] = __builtin_amdgcn_mfma_f32_32x32x16_bf16(vf, pf[kk], o[d0], 0, 0, 0);
;                 }
.LBB0_530:
	v_sub_f32_e32 v4, v94, v0
	v_exp_f32_e32 v13, v4
	v_sub_f32_e32 v4, v95, v0
	v_exp_f32_e32 v12, v4
	v_sub_f32_e32 v4, v110, v0
	v_exp_f32_e32 v14, v4
	v_sub_f32_e32 v4, v111, v0
	v_exp_f32_e32 v94, v4
	v_sub_f32_e32 v4, v92, v0
	v_exp_f32_e32 v95, v4
	v_sub_f32_e32 v4, v93, v0
	v_exp_f32_e32 v92, v4
	v_sub_f32_e32 v4, v108, v0
	v_exp_f32_e32 v93, v4
	v_sub_f32_e32 v4, v109, v0
	v_exp_f32_e32 v108, v4
	v_sub_f32_e32 v4, v90, v0
	v_exp_f32_e32 v109, v4
	v_sub_f32_e32 v4, v91, v0
	v_exp_f32_e32 v110, v4
	v_sub_f32_e32 v4, v106, v0
	v_exp_f32_e32 v111, v4
	v_sub_f32_e32 v4, v107, v0
	v_exp_f32_e32 v106, v4
	v_sub_f32_e32 v4, v88, v0
	v_exp_f32_e32 v107, v4
	v_sub_f32_e32 v4, v89, v0
	v_exp_f32_e32 v112, v4
	v_sub_f32_e32 v4, v104, v0
	v_exp_f32_e32 v113, v4
	v_sub_f32_e32 v4, v105, v0
	v_exp_f32_e32 v104, v4
	v_sub_f32_e32 v4, v86, v0
	v_exp_f32_e32 v105, v4
	v_sub_f32_e32 v4, v87, v0
	v_exp_f32_e32 v114, v4
	v_sub_f32_e32 v4, v102, v0
	v_exp_f32_e32 v115, v4
	v_sub_f32_e32 v4, v103, v0
	v_exp_f32_e32 v102, v4
	v_sub_f32_e32 v4, v84, v0
	v_exp_f32_e32 v103, v4
	v_sub_f32_e32 v4, v85, v0
	v_exp_f32_e32 v116, v4
	v_sub_f32_e32 v4, v100, v0
	v_exp_f32_e32 v117, v4
	v_sub_f32_e32 v4, v101, v0
	v_exp_f32_e32 v100, v4
	v_sub_f32_e32 v4, v82, v0
	v_exp_f32_e32 v101, v4
	v_sub_f32_e32 v4, v83, v0
	v_exp_f32_e32 v118, v4
	v_sub_f32_e32 v4, v98, v0
	v_exp_f32_e32 v119, v4
	v_sub_f32_e32 v4, v99, v0
	v_sub_f32_e32 v5, v96, v0
	v_exp_f32_e32 v98, v4
	v_sub_f32_e32 v4, v80, v0
	v_exp_f32_e32 v99, v5
	v_sub_f32_e32 v5, v97, v0
	v_sub_f32_e32 v0, v81, v0
	s_lshl_b64 s[0:1], s[0:1], 10
	v_exp_f32_e32 v96, v5
	v_exp_f32_e32 v97, v4
	v_exp_f32_e32 v0, v0
	s_add_u32 s0, s17, s0
	s_addc_u32 s1, s21, s1
	s_add_u32 s0, s0, s2
	s_addc_u32 s1, s1, s3
	v_add3_u32 v3, s5, v151, v150
	v_cvt_pk_bf16_f32 v4, v99, v96
	v_cvt_pk_bf16_f32 v5, v119, v98
	v_cvt_pk_bf16_f32 v6, v117, v100
	v_cvt_pk_bf16_f32 v7, v115, v102
	v_cvt_pk_bf16_f32 v8, v113, v104
	v_cvt_pk_bf16_f32 v9, v111, v106
	v_cvt_pk_bf16_f32 v10, v93, v108
	v_cvt_pk_bf16_f32 v11, v14, v94
	v_cvt_pk_bf16_f32 v80, v97, v0
	v_cvt_pk_bf16_f32 v81, v101, v118
	v_cvt_pk_bf16_f32 v82, v103, v116
	v_cvt_pk_bf16_f32 v83, v105, v114
	v_cvt_pk_bf16_f32 v84, v107, v112
	v_cvt_pk_bf16_f32 v85, v109, v110
	v_cvt_pk_bf16_f32 v86, v95, v92
	v_cvt_pk_bf16_f32 v87, v13, v12
	s_setprio 1
	ds_read_b128 v[88:91], v3 offset:17408
	ds_read_b128 v[168:171], v3 offset:17440
	ds_read_b128 v[172:175], v3 offset:17472
	ds_read_b128 v[176:179], v3 offset:17504
	ds_read_b128 v[180:183], v3 offset:22016
	ds_read_b128 v[184:187], v3 offset:22048
	ds_read_b128 v[188:191], v3 offset:22080
	ds_read_b128 v[192:195], v3 offset:22112
	ds_read_b128 v[204:207], v3 offset:26624
	ds_read_b128 v[208:211], v3 offset:26656
	ds_read_b128 v[212:215], v3 offset:26688
	ds_read_b128 v[216:219], v3 offset:26720
	ds_read_b128 v[220:223], v3 offset:31232
	ds_read_b128 v[224:227], v3 offset:31264
	ds_read_b128 v[120:123], v3 offset:31296
	s_waitcnt lgkmcnt(14)
	v_mfma_f32_32x32x16_bf16 v[64:79], v[88:91], v[4:7], v[64:79]
	ds_read_b128 v[124:127], v3 offset:31328
	s_waitcnt lgkmcnt(14)
	v_mfma_f32_32x32x16_bf16 v[64:79], v[168:171], v[8:11], v[64:79]
	s_waitcnt lgkmcnt(13)
	v_mfma_f32_32x32x16_bf16 v[64:79], v[172:175], v[80:83], v[64:79]
	s_waitcnt lgkmcnt(12)
	v_mfma_f32_32x32x16_bf16 v[64:79], v[176:179], v[84:87], v[64:79]
	s_waitcnt lgkmcnt(11)
	v_mfma_f32_32x32x16_bf16 v[48:63], v[180:183], v[4:7], v[48:63]
	s_waitcnt lgkmcnt(10)
	v_mfma_f32_32x32x16_bf16 v[48:63], v[184:187], v[8:11], v[48:63]
	s_waitcnt lgkmcnt(9)
	v_mfma_f32_32x32x16_bf16 v[48:63], v[188:191], v[80:83], v[48:63]
	s_waitcnt lgkmcnt(8)
	v_mfma_f32_32x32x16_bf16 v[48:63], v[192:195], v[84:87], v[48:63]
	s_waitcnt lgkmcnt(7)
	v_mfma_f32_32x32x16_bf16 v[32:47], v[204:207], v[4:7], v[32:47]
	s_waitcnt lgkmcnt(6)
	v_mfma_f32_32x32x16_bf16 v[32:47], v[208:211], v[8:11], v[32:47]
	s_waitcnt lgkmcnt(5)
	v_mfma_f32_32x32x16_bf16 v[32:47], v[212:215], v[80:83], v[32:47]
	s_waitcnt lgkmcnt(4)
	v_mfma_f32_32x32x16_bf16 v[32:47], v[216:219], v[84:87], v[32:47]
	s_waitcnt lgkmcnt(3)
	v_mfma_f32_32x32x16_bf16 v[16:31], v[220:223], v[4:7], v[16:31]
	s_waitcnt lgkmcnt(2)
	v_mfma_f32_32x32x16_bf16 v[16:31], v[224:227], v[8:11], v[16:31]
	s_waitcnt lgkmcnt(1)
	v_mfma_f32_32x32x16_bf16 v[16:31], v[120:123], v[80:83], v[16:31]
	s_waitcnt lgkmcnt(0)
; #define LAS __attribute__((address_space(3)))
; __device__ __forceinline__ unsigned pk2(float lo, float hi) { f32x2 v = {lo, hi}; bf16x2_t b = __builtin_convertvector(v, bf16x2_t); return __builtin_bit_cast(unsigned, b); }
; #define ATT_STORE(boff, KS, VS) do { _Pragma("unroll") for (int p = 0; p < NP; ++p) { *(LAS u32x4*)(lds + (boff) + kl[p]) = KS[p]; *(LAS u32x4*)(lds + (boff) + vl[p]) = VS[p]; } } while (0)
; #define ATT_STORE(b) do { _Pragma("unroll") for (int p = 0; p < NP; ++p) { *(LAS u32x4*)(lds + (b) * BUF + kl[p]) = kst[p]; *(LAS u32x4*)(lds + (b) * BUF + vl[p]) = vst[p]; } } while (0)
; template <int HD, int MODE> ...
;     ...
;             __builtin_amdgcn_s_setprio(1);
; #pragma unroll
;             for (int d0 = 0; d0 < HD / 32; ++d0)
; #pragma unroll
;                 for (int kk = 0; kk < 4; ++kk) {
;                     const bf16x8 vf = *(const LAS bf16x8*)(vb + d0 * 32 * VROW + kk * 32);
;                     o[d0] = __builtin_amdgcn_mfma_f32_32x32x16_bf16(vf, pf[kk], o[d0], 0, 0, 0);
;                 }
;             __builtin_amdgcn_s_setprio(0); }
;         }
;         if (more) ATT_STORE(cur ^ 1);
;         cur ^= 1;
;     }
;     float l_tot; { auto rr = __builtin_amdgcn_permlane32_swap(__float_as_uint(l_run), __float_as_uint(l_run), false, false); l_tot = __uint_as_float(rr[0]) + __uint_as_float(rr[1]); }
;     const float inv = 1.0f / l_tot;
;     gbf16* orow = Og + (size_t)(wid * 32 + r32) * o_pitch + 4 * hi;
; #pragma unroll
;     for (int d0 = 0; d0 < HD / 32; ++d0)
; #pragma unroll
;         for (int rq = 0; rq < 4; ++rq) { u32x2 w; w.x = pk2(o[d0][4 * rq] * inv, o[d0][4 * rq + 1] * inv); w.y = pk2(o[d0][4 * rq + 2] * inv, o[d0][4 * rq + 3] * inv);
;             *(gu32x2*)(orow + 32 * d0 + 8 * rq) = w; }
	v_mfma_f32_32x32x16_bf16 v[16:31], v[124:127], v[84:87], v[16:31]
	s_setprio 0
	v_add_f32_e32 v97, v99, v97
	v_add_f32_e64 v4, v96, v0
	v_add_f32_e64 v5, v97, v1
	v_add_f32_e32 v99, v119, v101
	v_pk_add_f32 v[4:5], v[4:5], v[4:5] op_sel_hi:[0,1]
	v_mov_b32_e32 v119, v5
	v_pk_add_f32 v[4:5], v[98:99], v[118:119]
	v_add_f32_e32 v101, v117, v103
	v_pk_add_f32 v[4:5], v[4:5], v[4:5] op_sel_hi:[0,1]
	v_mov_b32_e32 v117, v5
	v_pk_add_f32 v[4:5], v[100:101], v[116:117]
	v_add_f32_e32 v103, v115, v105
	v_pk_add_f32 v[4:5], v[4:5], v[4:5] op_sel_hi:[0,1]
	v_mov_b32_e32 v115, v5
	v_pk_add_f32 v[4:5], v[102:103], v[114:115]
	v_add_f32_e32 v105, v113, v107
	v_pk_add_f32 v[4:5], v[4:5], v[4:5] op_sel_hi:[0,1]
	v_mov_b32_e32 v113, v5
	v_pk_add_f32 v[4:5], v[104:105], v[112:113]
	v_add_f32_e32 v107, v111, v109
	v_pk_add_f32 v[4:5], v[4:5], v[4:5] op_sel_hi:[0,1]
	v_mov_b32_e32 v111, v5
	v_pk_add_f32 v[4:5], v[106:107], v[110:111]
	v_add_f32_e32 v109, v93, v95
	v_pk_add_f32 v[4:5], v[4:5], v[4:5] op_sel_hi:[0,1]
	v_mov_b32_e32 v93, v5
	v_pk_add_f32 v[4:5], v[108:109], v[92:93]
	v_add_f32_e32 v95, v14, v13
	v_pk_add_f32 v[4:5], v[4:5], v[4:5] op_sel_hi:[0,1]
	v_mov_b32_e32 v13, v5
	v_pk_add_f32 v[4:5], v[94:95], v[12:13]
	s_add_i32 s43, s43, s14
	v_add_f32_e32 v0, v4, v5
	v_fmac_f32_e32 v0, v15, v2
	v_mov_b32_e32 v2, v0
	s_nop 1
	v_permlane32_swap_b32_e32 v0, v2
	v_add_f32_e32 v0, v0, v2
	v_div_scale_f32 v2, s[2:3], v0, v0, 1.0
	v_rcp_f32_e32 v3, v2
	s_cmpk_gt_i32 s43, 0x1ff
	v_fma_f32 v4, -v2, v3, 1.0
	v_fmac_f32_e32 v3, v4, v3
	v_div_scale_f32 v4, vcc, 1.0, v0, 1.0
	v_mul_f32_e32 v5, v4, v3
	v_fma_f32 v6, -v2, v5, v4
	v_fmac_f32_e32 v5, v6, v3
	v_fma_f32 v2, -v2, v5, v4
	v_div_fmas_f32 v2, v2, v3, v5
	v_div_fixup_f32 v2, v2, v0, 1.0
	v_lshlrev_b64 v[4:5], 10, v[148:149]
	v_lshl_add_u64 v[4:5], s[0:1], 0, v[4:5]
	v_lshlrev_b32_e32 v0, 3, v164
	v_pk_mul_f32 v[6:7], v[64:65], v[2:3] op_sel_hi:[1,0]
	v_pk_mul_f32 v[8:9], v[66:67], v[2:3] op_sel_hi:[1,0]
	v_lshl_add_u64 v[4:5], v[4:5], 0, v[0:1]
	v_cvt_pk_bf16_f32 v6, v6, v7
	v_cvt_pk_bf16_f32 v7, v8, v9
	global_store_dwordx2 v[4:5], v[6:7], off
	v_pk_mul_f32 v[6:7], v[68:69], v[2:3] op_sel_hi:[1,0]
	v_pk_mul_f32 v[8:9], v[70:71], v[2:3] op_sel_hi:[1,0]
	v_cvt_pk_bf16_f32 v6, v6, v7
	v_cvt_pk_bf16_f32 v7, v8, v9
	global_store_dwordx2 v[4:5], v[6:7], off offset:16
	v_pk_mul_f32 v[6:7], v[72:73], v[2:3] op_sel_hi:[1,0]
	v_pk_mul_f32 v[8:9], v[74:75], v[2:3] op_sel_hi:[1,0]
	v_cvt_pk_bf16_f32 v6, v6, v7
	v_cvt_pk_bf16_f32 v7, v8, v9
	global_store_dwordx2 v[4:5], v[6:7], off offset:32
	v_pk_mul_f32 v[6:7], v[76:77], v[2:3] op_sel_hi:[1,0]
	v_pk_mul_f32 v[8:9], v[78:79], v[2:3] op_sel_hi:[1,0]
	v_cvt_pk_bf16_f32 v6, v6, v7
	v_cvt_pk_bf16_f32 v7, v8, v9
	global_store_dwordx2 v[4:5], v[6:7], off offset:48
	v_pk_mul_f32 v[6:7], v[48:49], v[2:3] op_sel_hi:[1,0]
	v_pk_mul_f32 v[8:9], v[50:51], v[2:3] op_sel_hi:[1,0]
	v_cvt_pk_bf16_f32 v6, v6, v7
	v_cvt_pk_bf16_f32 v7, v8, v9
	global_store_dwordx2 v[4:5], v[6:7], off offset:64
	v_pk_mul_f32 v[6:7], v[52:53], v[2:3] op_sel_hi:[1,0]
	v_pk_mul_f32 v[8:9], v[54:55], v[2:3] op_sel_hi:[1,0]
	v_cvt_pk_bf16_f32 v6, v6, v7
	v_cvt_pk_bf16_f32 v7, v8, v9
	global_store_dwordx2 v[4:5], v[6:7], off offset:80
	v_pk_mul_f32 v[6:7], v[56:57], v[2:3] op_sel_hi:[1,0]
	v_pk_mul_f32 v[8:9], v[58:59], v[2:3] op_sel_hi:[1,0]
	v_cvt_pk_bf16_f32 v6, v6, v7
	v_cvt_pk_bf16_f32 v7, v8, v9
	global_store_dwordx2 v[4:5], v[6:7], off offset:96
	v_pk_mul_f32 v[6:7], v[60:61], v[2:3] op_sel_hi:[1,0]
	v_pk_mul_f32 v[8:9], v[62:63], v[2:3] op_sel_hi:[1,0]
	v_cvt_pk_bf16_f32 v6, v6, v7
	v_cvt_pk_bf16_f32 v7, v8, v9
	global_store_dwordx2 v[4:5], v[6:7], off offset:112
	v_pk_mul_f32 v[6:7], v[32:33], v[2:3] op_sel_hi:[1,0]
	v_pk_mul_f32 v[8:9], v[34:35], v[2:3] op_sel_hi:[1,0]
	v_cvt_pk_bf16_f32 v6, v6, v7
	v_cvt_pk_bf16_f32 v7, v8, v9
	global_store_dwordx2 v[4:5], v[6:7], off offset:128
	v_pk_mul_f32 v[6:7], v[36:37], v[2:3] op_sel_hi:[1,0]
	v_pk_mul_f32 v[8:9], v[38:39], v[2:3] op_sel_hi:[1,0]
	v_cvt_pk_bf16_f32 v6, v6, v7
	v_cvt_pk_bf16_f32 v7, v8, v9
	global_store_dwordx2 v[4:5], v[6:7], off offset:144
	v_pk_mul_f32 v[6:7], v[40:41], v[2:3] op_sel_hi:[1,0]
	v_pk_mul_f32 v[8:9], v[42:43], v[2:3] op_sel_hi:[1,0]
	v_cvt_pk_bf16_f32 v6, v6, v7
	v_cvt_pk_bf16_f32 v7, v8, v9
	global_store_dwordx2 v[4:5], v[6:7], off offset:160
	v_pk_mul_f32 v[6:7], v[44:45], v[2:3] op_sel_hi:[1,0]
	v_pk_mul_f32 v[8:9], v[46:47], v[2:3] op_sel_hi:[1,0]
	v_cvt_pk_bf16_f32 v6, v6, v7
	v_cvt_pk_bf16_f32 v7, v8, v9
	global_store_dwordx2 v[4:5], v[6:7], off offset:176
	v_pk_mul_f32 v[6:7], v[16:17], v[2:3] op_sel_hi:[1,0]
	v_pk_mul_f32 v[8:9], v[18:19], v[2:3] op_sel_hi:[1,0]
	v_cvt_pk_bf16_f32 v6, v6, v7
	v_cvt_pk_bf16_f32 v7, v8, v9
	global_store_dwordx2 v[4:5], v[6:7], off offset:192
	v_pk_mul_f32 v[6:7], v[20:21], v[2:3] op_sel_hi:[1,0]
	v_pk_mul_f32 v[8:9], v[22:23], v[2:3] op_sel_hi:[1,0]
	v_cvt_pk_bf16_f32 v6, v6, v7
	v_cvt_pk_bf16_f32 v7, v8, v9
	global_store_dwordx2 v[4:5], v[6:7], off offset:208
	v_pk_mul_f32 v[6:7], v[24:25], v[2:3] op_sel_hi:[1,0]
	v_pk_mul_f32 v[8:9], v[26:27], v[2:3] op_sel_hi:[1,0]
	v_cvt_pk_bf16_f32 v6, v6, v7
	v_cvt_pk_bf16_f32 v7, v8, v9
	global_store_dwordx2 v[4:5], v[6:7], off offset:224
	v_pk_mul_f32 v[6:7], v[28:29], v[2:3] op_sel_hi:[1,0]
	v_pk_mul_f32 v[2:3], v[30:31], v[2:3] op_sel_hi:[1,0]
	v_cvt_pk_bf16_f32 v6, v6, v7
	v_cvt_pk_bf16_f32 v7, v2, v3
	global_store_dwordx2 v[4:5], v[6:7], off offset:240
	s_cbranch_scc1 .LBB0_538

; #define LAS __attribute__((address_space(3)))
; template <int HD, int MODE> ...
;     ...
;             __builtin_amdgcn_s_setprio(1);
; #pragma unroll
;             for (int d0 = 0; d0 < HD / 16; ++d0) {
;                 const bf16x8 k0 = *(const LAS bf16x8*)(kb + d0 * 32);
;                 const bf16x8 k1 = *(const LAS bf16x8*)(kb + 32 * KROW + d0 * 32);
;                 s0 = __builtin_amdgcn_mfma_f32_32x32x16_bf16(k0, qf[d0], s0, 0, 0, 0);
;                 s1 = __builtin_amdgcn_mfma_f32_32x32x16_bf16(k1, qf[d0], s1, 0, 0, 0);
;             }
;             __builtin_amdgcn_s_setprio(0); }
;             if (MODE == 1) {
;                 const LAS float* bl = biasl + (64 * t + 8 * hi - (qlo + r32) + 384);
; #pragma unroll
;                 for (int r = 0; r < 16; ++r) { s0[r] += bl[16 * (r >> 3) + (r & 7)]; s1[r] += bl[32 + 16 * (r >> 3) + (r & 7)]; }
;             }
;             float mx = fmaxf(s0[0], s1[0]);
; #pragma unroll
;             for (int r = 1; r < 16; ++r) mx = fmaxf(mx, fmaxf(s0[r], s1[r]));
;             { auto rr = __builtin_amdgcn_permlane32_swap(__float_as_uint(mx), __float_as_uint(mx), false, false); mx = fmaxf(__uint_as_float(rr[0]), __uint_as_float(rr[1])); }
;             const float m_new = fmaxf(m_run, mx);
;             const bool grew = __any(m_new > m_run);
;             const float alpha = __builtin_amdgcn_exp2f(m_run - m_new);
;             m_run = m_new;
;             float rs = 0.f;
; #pragma unroll
;             for (int r = 0; r < 16; ++r) { s0[r] = __builtin_amdgcn_exp2f(s0[r] - m_new); s1[r] = __builtin_amdgcn_exp2f(s1[r] - m_new); rs += s0[r] + s1[r]; }
;             l_run = l_run * alpha + rs;
;             if (grew) {
; #pragma unroll
;                 for (int d0 = 0; d0 < HD / 32; ++d0)
; #pragma unroll
;                     for (int r = 0; r < 16; ++r) o[d0][r] *= alpha;
;             }
.LBB0_532:
	v_lshl_add_u64 v[2:3], s[84:85], 0, v[162:163]
	v_lshl_add_u64 v[4:5], s[84:85], 0, v[158:159]
	v_lshl_add_u64 v[10:11], s[84:85], 0, v[160:161]
	v_lshl_add_u64 v[12:13], s[84:85], 0, v[156:157]
	s_waitcnt lgkmcnt(0)
	s_barrier
	global_load_dwordx4 v[6:9], v[2:3], off
	s_nop 0
	global_load_dwordx4 v[2:5], v[4:5], off
	s_nop 0
	global_load_dwordx4 v[144:147], v[10:11], off
	s_nop 0
	global_load_dwordx4 v[10:13], v[12:13], off
	s_mul_i32 s5, s4, 0x8c00
	s_add_i32 s5, s5, 0
	v_add3_u32 v14, s5, v167, v150
	v_mov_b32_e32 v0, v153
	s_setprio 1
	ds_read_b128 v[80:83], v14
	ds_read_b128 v[168:171], v14 offset:32
	ds_read_b128 v[96:99], v14 offset:8704
	ds_read_b128 v[172:175], v14 offset:8736
	ds_read_b128 v[176:179], v14 offset:64
	ds_read_b128 v[180:183], v14 offset:8768
	ds_read_b128 v[184:187], v14 offset:96
	ds_read_b128 v[188:191], v14 offset:8800
	ds_read_b128 v[192:195], v14 offset:128
	ds_read_b128 v[204:207], v14 offset:8832
	ds_read_b128 v[208:211], v14 offset:160
	ds_read_b128 v[212:215], v14 offset:8864
	ds_read_b128 v[216:219], v14 offset:192
	ds_read_b128 v[220:223], v14 offset:8896
	ds_read_b128 v[224:227], v14 offset:224
	s_waitcnt lgkmcnt(14)
	v_mfma_f32_32x32x16_bf16 v[80:95], v[80:83], v[140:143], 0
	s_waitcnt lgkmcnt(13)
	v_mfma_f32_32x32x16_bf16 v[80:95], v[168:171], v[136:139], v[80:95]
	ds_read_b128 v[168:171], v14 offset:8928
	s_waitcnt lgkmcnt(13)
	v_mfma_f32_32x32x16_bf16 v[96:111], v[96:99], v[140:143], 0
	s_waitcnt lgkmcnt(12)
	v_mfma_f32_32x32x16_bf16 v[96:111], v[172:175], v[136:139], v[96:111]
	s_waitcnt lgkmcnt(11)
	v_mfma_f32_32x32x16_bf16 v[80:95], v[176:179], v[132:135], v[80:95]
	s_waitcnt lgkmcnt(10)
	v_mfma_f32_32x32x16_bf16 v[96:111], v[180:183], v[132:135], v[96:111]
	s_waitcnt lgkmcnt(9)
	v_mfma_f32_32x32x16_bf16 v[80:95], v[184:187], v[128:131], v[80:95]
	s_waitcnt lgkmcnt(8)
	v_mfma_f32_32x32x16_bf16 v[96:111], v[188:191], v[128:131], v[96:111]
	s_waitcnt lgkmcnt(7)
	v_mfma_f32_32x32x16_bf16 v[80:95], v[192:195], v[124:127], v[80:95]
	s_waitcnt lgkmcnt(6)
	v_mfma_f32_32x32x16_bf16 v[96:111], v[204:207], v[124:127], v[96:111]
	s_waitcnt lgkmcnt(5)
	v_mfma_f32_32x32x16_bf16 v[80:95], v[208:211], v[120:123], v[80:95]
	s_waitcnt lgkmcnt(4)
	v_mfma_f32_32x32x16_bf16 v[96:111], v[212:215], v[120:123], v[96:111]
	s_waitcnt lgkmcnt(3)
	v_mfma_f32_32x32x16_bf16 v[80:95], v[216:219], v[116:119], v[80:95]
	s_waitcnt lgkmcnt(2)
	v_mfma_f32_32x32x16_bf16 v[96:111], v[220:223], v[116:119], v[96:111]
	s_waitcnt lgkmcnt(1)
	v_mfma_f32_32x32x16_bf16 v[80:95], v[224:227], v[112:115], v[80:95]
	s_waitcnt lgkmcnt(0)
	v_mfma_f32_32x32x16_bf16 v[96:111], v[168:171], v[112:115], v[96:111]
	s_setprio 0
	s_nop 10
	v_max_f32_e32 v14, v97, v97
	v_max_f32_e32 v15, v81, v81
	v_max_f32_e32 v14, v15, v14
	v_max_f32_e32 v15, v98, v98
	v_max_f32_e32 v153, v82, v82
	v_max_f32_e32 v15, v153, v15
	v_max_f32_e32 v153, v99, v99
	v_max_f32_e32 v168, v83, v83
	v_max3_f32 v14, v80, v96, v14
	v_max_f32_e32 v153, v168, v153
	v_max3_f32 v14, v14, v15, v153
	v_max_f32_e32 v15, v100, v100
	v_max_f32_e32 v153, v84, v84
	v_max_f32_e32 v15, v153, v15
	v_max_f32_e32 v153, v101, v101
	v_max_f32_e32 v168, v85, v85
	v_max_f32_e32 v153, v168, v153
	v_max3_f32 v14, v14, v15, v153
	v_max_f32_e32 v15, v102, v102
	v_max_f32_e32 v153, v86, v86
	v_max_f32_e32 v15, v153, v15
	v_max_f32_e32 v153, v103, v103
	v_max_f32_e32 v168, v87, v87
	v_max_f32_e32 v153, v168, v153
	v_max3_f32 v14, v14, v15, v153
	v_max_f32_e32 v15, v104, v104
	v_max_f32_e32 v153, v88, v88
	v_max_f32_e32 v15, v153, v15
	v_max_f32_e32 v153, v105, v105
	v_max_f32_e32 v168, v89, v89
	v_max_f32_e32 v153, v168, v153
	v_max3_f32 v14, v14, v15, v153
	v_max_f32_e32 v15, v106, v106
	v_max_f32_e32 v153, v90, v90
	v_max_f32_e32 v15, v153, v15
	v_max_f32_e32 v153, v107, v107
	v_max_f32_e32 v168, v91, v91
	v_max_f32_e32 v153, v168, v153
	v_max3_f32 v14, v14, v15, v153
	v_max_f32_e32 v15, v108, v108
	v_max_f32_e32 v153, v92, v92
	v_max_f32_e32 v15, v153, v15
	v_max_f32_e32 v153, v109, v109
	v_max_f32_e32 v168, v93, v93
	v_max_f32_e32 v153, v168, v153
	v_max3_f32 v14, v14, v15, v153
	v_max_f32_e32 v15, v110, v110
	v_max_f32_e32 v153, v94, v94
	v_max_f32_e32 v15, v153, v15
	v_max_f32_e32 v153, v111, v111
	v_max_f32_e32 v168, v95, v95
	v_max_f32_e32 v153, v168, v153
	v_max3_f32 v14, v14, v15, v153
	v_mov_b32_e32 v15, v14
	s_nop 1
	v_permlane32_swap_b32_e32 v14, v15
	v_max3_f32 v153, v0, v14, v15
	v_sub_f32_e32 v14, v0, v153
	v_exp_f32_e32 v14, v14
	v_cmp_gt_f32_e32 vcc, v153, v0
	s_cbranch_vccz .LBB0_534
	v_pk_mul_f32 v[78:79], v[78:79], v[14:15] op_sel_hi:[1,0]
	v_pk_mul_f32 v[76:77], v[76:77], v[14:15] op_sel_hi:[1,0]
	v_pk_mul_f32 v[74:75], v[74:75], v[14:15] op_sel_hi:[1,0]
	v_pk_mul_f32 v[72:73], v[72:73], v[14:15] op_sel_hi:[1,0]
	v_pk_mul_f32 v[70:71], v[70:71], v[14:15] op_sel_hi:[1,0]
	v_pk_mul_f32 v[68:69], v[68:69], v[14:15] op_sel_hi:[1,0]
	v_pk_mul_f32 v[66:67], v[66:67], v[14:15] op_sel_hi:[1,0]
	v_pk_mul_f32 v[64:65], v[64:65], v[14:15] op_sel_hi:[1,0]
	v_pk_mul_f32 v[62:63], v[62:63], v[14:15] op_sel_hi:[1,0]
	v_pk_mul_f32 v[60:61], v[60:61], v[14:15] op_sel_hi:[1,0]
	v_pk_mul_f32 v[58:59], v[58:59], v[14:15] op_sel_hi:[1,0]
	v_pk_mul_f32 v[56:57], v[56:57], v[14:15] op_sel_hi:[1,0]
	v_pk_mul_f32 v[54:55], v[54:55], v[14:15] op_sel_hi:[1,0]
	v_pk_mul_f32 v[52:53], v[52:53], v[14:15] op_sel_hi:[1,0]
	v_pk_mul_f32 v[50:51], v[50:51], v[14:15] op_sel_hi:[1,0]
	v_pk_mul_f32 v[48:49], v[48:49], v[14:15] op_sel_hi:[1,0]
	v_pk_mul_f32 v[46:47], v[46:47], v[14:15] op_sel_hi:[1,0]
	v_pk_mul_f32 v[44:45], v[44:45], v[14:15] op_sel_hi:[1,0]
	v_pk_mul_f32 v[42:43], v[42:43], v[14:15] op_sel_hi:[1,0]
	v_pk_mul_f32 v[40:41], v[40:41], v[14:15] op_sel_hi:[1,0]
	v_pk_mul_f32 v[38:39], v[38:39], v[14:15] op_sel_hi:[1,0]
	v_pk_mul_f32 v[36:37], v[36:37], v[14:15] op_sel_hi:[1,0]
	v_pk_mul_f32 v[34:35], v[34:35], v[14:15] op_sel_hi:[1,0]
	v_pk_mul_f32 v[32:33], v[32:33], v[14:15] op_sel_hi:[1,0]
	v_pk_mul_f32 v[30:31], v[30:31], v[14:15] op_sel_hi:[1,0]
	v_pk_mul_f32 v[28:29], v[28:29], v[14:15] op_sel_hi:[1,0]
	v_pk_mul_f32 v[26:27], v[26:27], v[14:15] op_sel_hi:[1,0]
	v_pk_mul_f32 v[24:25], v[24:25], v[14:15] op_sel_hi:[1,0]
	v_pk_mul_f32 v[22:23], v[22:23], v[14:15] op_sel_hi:[1,0]
	v_pk_mul_f32 v[20:21], v[20:21], v[14:15] op_sel_hi:[1,0]
	v_pk_mul_f32 v[18:19], v[18:19], v[14:15] op_sel_hi:[1,0]
	v_pk_mul_f32 v[16:17], v[16:17], v[14:15] op_sel_hi:[1,0]
; template <int HD, int MODE> ...
;     ...
;             const float alpha = __builtin_amdgcn_exp2f(m_run - m_new);
;             m_run = m_new;
;             float rs = 0.f;
; #pragma unroll
;             for (int r = 0; r < 16; ++r) { s0[r] = __builtin_amdgcn_exp2f(s0[r] - m_new); s1[r] = __builtin_amdgcn_exp2f(s1[r] - m_new); rs += s0[r] + s1[r]; }
;             l_run = l_run * alpha + rs;
;             if (grew) {
; #pragma unroll
;                 for (int d0 = 0; d0 < HD / 32; ++d0)
; #pragma unroll
;                     for (int r = 0; r < 16; ++r) o[d0][r] *= alpha;
;             }
;             bf16x8 pf[4];
;             { u32x4 w;
;               w.x = pk2(s0[0], s0[1]); w.y = pk2(s0[2], s0[3]); w.z = pk2(s0[4], s0[5]); w.w = pk2(s0[6], s0[7]); pf[0] = __builtin_bit_cast(bf16x8, w);
;               w.x = pk2(s0[8], s0[9]); w.y = pk2(s0[10], s0[11]); w.z = pk2(s0[12], s0[13]); w.w = pk2(s0[14], s0[15]); pf[1] = __builtin_bit_cast(bf16x8, w);
;               w.x = pk2(s1[0], s1[1]); w.y = pk2(s1[2], s1[3]); w.z = pk2(s1[4], s1[5]); w.w = pk2(s1[6], s1[7]); pf[2] = __builtin_bit_cast(bf16x8, w);
;               w.x = pk2(s1[8], s1[9]); w.y = pk2(s1[10], s1[11]); w.z = pk2(s1[12], s1[13]); w.w = pk2(s1[14], s1[15]); pf[3] = __builtin_bit_cast(bf16x8, w); }
;             if constexpr (HD == 64) {
;                 bf16x8 vfr[HD / 32][4];
; #pragma unroll
;                 for (int d0 = 0; d0 < HD / 32; ++d0)
; #pragma unroll
;                     for (int kk = 0; kk < 4; ++kk) vfr[d0][kk] = *(const LAS bf16x8*)(vb + d0 * 32 * VROW + kk * 32);
;                 __builtin_amdgcn_sched_barrier(0);
;                 __builtin_amdgcn_s_setprio(1);
; #pragma unroll
;                 for (int d0 = 0; d0 < HD / 32; ++d0)
; #pragma unroll
;                     for (int kk = 0; kk < 4; ++kk) o[d0] = __builtin_amdgcn_mfma_f32_32x32x16_bf16(vfr[d0][kk], pf[kk], o[d0], 0, 0, 0);
;                 __builtin_amdgcn_s_setprio(0);
;             } else {
;             __builtin_amdgcn_s_setprio(1);
; #pragma unroll
;             for (int d0 = 0; d0 < HD / 32; ++d0)
; #pragma unroll
;                 for (int kk = 0; kk < 4; ++kk) {
;                     const bf16x8 vf = *(const LAS bf16x8*)(vb + d0 * 32 * VROW + kk * 32);
;                     o[d0] = __builtin_amdgcn_mfma_f32_32x32x16_bf16(vf, pf[kk], o[d0], 0, 0, 0);
;                 }
.LBB0_534:
	v_sub_f32_e32 v0, v80, v153
	v_exp_f32_e32 v168, v0
	v_sub_f32_e32 v0, v96, v153
	v_exp_f32_e32 v169, v0
	v_sub_f32_e32 v0, v81, v153
	v_exp_f32_e32 v80, v0
	v_sub_f32_e32 v0, v97, v153
	v_exp_f32_e32 v0, v0
	v_add_f32_e32 v81, v168, v169
	v_sub_f32_e32 v15, v82, v153
	v_pk_add_f32 v[96:97], v[80:81], v[0:1]
	v_exp_f32_e32 v81, v15
	v_sub_f32_e32 v15, v98, v153
	v_exp_f32_e32 v170, v15
	v_sub_f32_e32 v15, v83, v153
	v_pk_add_f32 v[96:97], v[96:97], v[96:97] op_sel_hi:[0,1]
	v_exp_f32_e32 v82, v15
	v_sub_f32_e32 v15, v99, v153
	v_exp_f32_e32 v96, v15
	v_add_f32_e32 v83, v81, v170
	v_sub_f32_e32 v15, v84, v153
	v_cvt_pk_bf16_f32 v80, v168, v80
	v_pk_add_f32 v[98:99], v[82:83], v[96:97]
	v_exp_f32_e32 v83, v15
	v_sub_f32_e32 v15, v100, v153
	v_exp_f32_e32 v97, v15
	v_sub_f32_e32 v15, v85, v153
	v_pk_add_f32 v[98:99], v[98:99], v[98:99] op_sel_hi:[0,1]
	v_exp_f32_e32 v84, v15
	v_sub_f32_e32 v15, v101, v153
	v_exp_f32_e32 v98, v15
	v_add_f32_e32 v85, v83, v97
	v_sub_f32_e32 v15, v86, v153
	v_cvt_pk_bf16_f32 v81, v81, v82
	v_pk_add_f32 v[100:101], v[84:85], v[98:99]
	v_exp_f32_e32 v85, v15
	v_sub_f32_e32 v15, v102, v153
	v_exp_f32_e32 v99, v15
	v_sub_f32_e32 v15, v87, v153
	v_pk_add_f32 v[100:101], v[100:101], v[100:101] op_sel_hi:[0,1]
	v_exp_f32_e32 v86, v15
	v_sub_f32_e32 v15, v103, v153
	v_exp_f32_e32 v100, v15
	v_add_f32_e32 v87, v85, v99
	v_sub_f32_e32 v15, v88, v153
	v_cvt_pk_bf16_f32 v82, v83, v84
	v_pk_add_f32 v[102:103], v[86:87], v[100:101]
	v_exp_f32_e32 v87, v15
	v_sub_f32_e32 v15, v104, v153
	v_exp_f32_e32 v101, v15
	v_sub_f32_e32 v15, v89, v153
	v_pk_add_f32 v[102:103], v[102:103], v[102:103] op_sel_hi:[0,1]
	v_exp_f32_e32 v88, v15
	v_sub_f32_e32 v15, v105, v153
	v_exp_f32_e32 v102, v15
	v_add_f32_e32 v89, v87, v101
	v_sub_f32_e32 v15, v90, v153
	v_cvt_pk_bf16_f32 v83, v85, v86
	v_pk_add_f32 v[104:105], v[88:89], v[102:103]
	v_exp_f32_e32 v89, v15
	v_sub_f32_e32 v15, v106, v153
	v_exp_f32_e32 v103, v15
	v_sub_f32_e32 v15, v91, v153
	v_pk_add_f32 v[104:105], v[104:105], v[104:105] op_sel_hi:[0,1]
	v_exp_f32_e32 v90, v15
	v_sub_f32_e32 v15, v107, v153
	v_exp_f32_e32 v104, v15
	v_add_f32_e32 v91, v89, v103
	v_sub_f32_e32 v15, v92, v153
	v_cvt_pk_bf16_f32 v84, v87, v88
	v_pk_add_f32 v[106:107], v[90:91], v[104:105]
	v_exp_f32_e32 v91, v15
	v_sub_f32_e32 v15, v108, v153
	v_exp_f32_e32 v105, v15
	v_sub_f32_e32 v15, v93, v153
	v_pk_add_f32 v[106:107], v[106:107], v[106:107] op_sel_hi:[0,1]
	v_exp_f32_e32 v92, v15
	v_sub_f32_e32 v15, v109, v153
	v_exp_f32_e32 v106, v15
	v_add_f32_e32 v93, v91, v105
	v_sub_f32_e32 v15, v94, v153
	v_cvt_pk_bf16_f32 v85, v89, v90
	v_pk_add_f32 v[108:109], v[92:93], v[106:107]
	v_exp_f32_e32 v93, v15
	v_sub_f32_e32 v15, v110, v153
	v_exp_f32_e32 v107, v15
	v_sub_f32_e32 v15, v95, v153
	v_pk_add_f32 v[108:109], v[108:109], v[108:109] op_sel_hi:[0,1]
	v_exp_f32_e32 v94, v15
	v_sub_f32_e32 v15, v111, v153
	v_exp_f32_e32 v108, v15
	v_add_f32_e32 v95, v93, v107
	v_cvt_pk_bf16_f32 v86, v91, v92
	v_cvt_pk_bf16_f32 v87, v93, v94
	v_pk_add_f32 v[110:111], v[94:95], v[108:109]
	v_cvt_pk_bf16_f32 v88, v169, v0
	v_add_f32_e32 v15, v110, v111
	v_fmac_f32_e32 v15, v155, v14
	v_cvt_pk_bf16_f32 v89, v170, v96
	v_cvt_pk_bf16_f32 v90, v97, v98
	v_cvt_pk_bf16_f32 v91, v99, v100
	v_cvt_pk_bf16_f32 v92, v101, v102
	v_cvt_pk_bf16_f32 v93, v103, v104
	v_cvt_pk_bf16_f32 v94, v105, v106
	v_cvt_pk_bf16_f32 v95, v107, v108
	s_setprio 1
	v_add3_u32 v0, s5, v151, v150
	ds_read_b128 v[96:99], v0 offset:17408
	ds_read_b128 v[100:103], v0 offset:17440
	ds_read_b128 v[104:107], v0 offset:17472
	ds_read_b128 v[108:111], v0 offset:17504
	ds_read_b128 v[168:171], v0 offset:22016
	ds_read_b128 v[172:175], v0 offset:22048
	ds_read_b128 v[176:179], v0 offset:22080
	ds_read_b128 v[180:183], v0 offset:22112
	ds_read_b128 v[184:187], v0 offset:26624
	ds_read_b128 v[188:191], v0 offset:26656
	ds_read_b128 v[192:195], v0 offset:26688
	ds_read_b128 v[204:207], v0 offset:26720
	ds_read_b128 v[208:211], v0 offset:31232
	ds_read_b128 v[212:215], v0 offset:31264
	ds_read_b128 v[216:219], v0 offset:31296
	s_waitcnt lgkmcnt(14)
	v_mfma_f32_32x32x16_bf16 v[64:79], v[96:99], v[80:83], v[64:79]
	ds_read_b128 v[220:223], v0 offset:31328
	s_waitcnt lgkmcnt(14)
	v_mfma_f32_32x32x16_bf16 v[64:79], v[100:103], v[84:87], v[64:79]
	s_waitcnt lgkmcnt(13)
	v_mfma_f32_32x32x16_bf16 v[64:79], v[104:107], v[88:91], v[64:79]
	s_waitcnt lgkmcnt(12)
	v_mfma_f32_32x32x16_bf16 v[64:79], v[108:111], v[92:95], v[64:79]
	s_waitcnt lgkmcnt(11)
	v_mfma_f32_32x32x16_bf16 v[48:63], v[168:171], v[80:83], v[48:63]
	s_waitcnt lgkmcnt(10)
	v_mfma_f32_32x32x16_bf16 v[48:63], v[172:175], v[84:87], v[48:63]
	s_waitcnt lgkmcnt(9)
	v_mfma_f32_32x32x16_bf16 v[48:63], v[176:179], v[88:91], v[48:63]
	s_waitcnt lgkmcnt(8)
	v_mfma_f32_32x32x16_bf16 v[48:63], v[180:183], v[92:95], v[48:63]
	s_waitcnt lgkmcnt(7)
	v_mfma_f32_32x32x16_bf16 v[32:47], v[184:187], v[80:83], v[32:47]
	s_waitcnt lgkmcnt(6)
	v_mfma_f32_32x32x16_bf16 v[32:47], v[188:191], v[84:87], v[32:47]
	s_waitcnt lgkmcnt(5)
	v_mfma_f32_32x32x16_bf16 v[32:47], v[192:195], v[88:91], v[32:47]
	s_waitcnt lgkmcnt(4)
	v_mfma_f32_32x32x16_bf16 v[32:47], v[204:207], v[92:95], v[32:47]
	s_waitcnt lgkmcnt(3)
	v_mfma_f32_32x32x16_bf16 v[16:31], v[208:211], v[80:83], v[16:31]
	s_waitcnt lgkmcnt(2)
	v_mfma_f32_32x32x16_bf16 v[16:31], v[212:215], v[84:87], v[16:31]
	s_waitcnt lgkmcnt(1)
	v_mfma_f32_32x32x16_bf16 v[16:31], v[216:219], v[88:91], v[16:31]
	s_waitcnt lgkmcnt(0)
	v_mfma_f32_32x32x16_bf16 v[16:31], v[220:223], v[92:95], v[16:31]
	s_setprio 0
	s_xor_b32 s4, s4, 1
	s_mul_i32 s5, s4, 0x8c00
	s_add_i32 s5, s5, 0
	v_add_u32_e32 v0, s5, v165
	s_waitcnt vmcnt(3)
	ds_write_b128 v0, v[6:9]
	v_add_u32_e32 v0, s5, v152
	s_waitcnt vmcnt(2)
	ds_write_b128 v0, v[2:5] offset:17408
	v_add_u32_e32 v0, s5, v166
	s_add_i32 s29, s29, -1
	s_waitcnt vmcnt(1)
	ds_write_b128 v0, v[144:147]
	v_add_u32_e32 v0, s5, v154
	v_lshl_add_u64 v[156:157], v[156:157], 0, s[68:69]
	v_lshl_add_u64 v[158:159], v[158:159], 0, s[68:69]
	v_lshl_add_u64 v[160:161], v[160:161], 0, s[80:81]
	s_cmp_eq_u32 s29, 0
	v_lshl_add_u64 v[162:163], v[162:163], 0, s[80:81]
	s_waitcnt vmcnt(0)
	ds_write_b128 v0, v[10:13] offset:17408
	s_cbranch_scc1 .LBB0_536
	v_mov_b32_e32 v155, v15
	s_branch .LBB0_532
; #define LAS __attribute__((address_space(3)))
; template <int HD, int MODE> ...
;     ...
;             __builtin_amdgcn_s_setprio(1);
; #pragma unroll
;             for (int d0 = 0; d0 < HD / 16; ++d0) {
;                 const bf16x8 k0 = *(const LAS bf16x8*)(kb + d0 * 32);
;                 const bf16x8 k1 = *(const LAS bf16x8*)(kb + 32 * KROW + d0 * 32);
;                 s0 = __builtin_amdgcn_mfma_f32_32x32x16_bf16(k0, qf[d0], s0, 0, 0, 0);
;                 s1 = __builtin_amdgcn_mfma_f32_32x32x16_bf16(k1, qf[d0], s1, 0, 0, 0);
;             }
;             __builtin_amdgcn_s_setprio(0); }
;             if (MODE == 1) {
;                 const LAS float* bl = biasl + (64 * t + 8 * hi - (qlo + r32) + 384);
; #pragma unroll
;                 for (int r = 0; r < 16; ++r) { s0[r] += bl[16 * (r >> 3) + (r & 7)]; s1[r] += bl[32 + 16 * (r >> 3) + (r & 7)]; }
;             }
;             float mx = fmaxf(s0[0], s1[0]);
; #pragma unroll
;             for (int r = 1; r < 16; ++r) mx = fmaxf(mx, fmaxf(s0[r], s1[r]));
;             { auto rr = __builtin_amdgcn_permlane32_swap(__float_as_uint(mx), __float_as_uint(mx), false, false); mx = fmaxf(__uint_as_float(rr[0]), __uint_as_float(rr[1])); }
;             const float m_new = fmaxf(m_run, mx);
;             const bool grew = __any(m_new > m_run);
;             const float alpha = __builtin_amdgcn_exp2f(m_run - m_new);
;             m_run = m_new;
;             float rs = 0.f;
; #pragma unroll
;             for (int r = 0; r < 16; ++r) { s0[r] = __builtin_amdgcn_exp2f(s0[r] - m_new); s1[r] = __builtin_amdgcn_exp2f(s1[r] - m_new); rs += s0[r] + s1[r]; }
;             l_run = l_run * alpha + rs;
;             if (grew) {
; #pragma unroll
;                 for (int d0 = 0; d0 < HD / 32; ++d0)
; #pragma unroll
;                     for (int r = 0; r < 16; ++r) o[d0][r] *= alpha;
;             }
.LBB0_536:
	v_add3_u32 v0, s5, v167, v150
	s_waitcnt lgkmcnt(0)
	s_barrier
	s_setprio 1
	ds_read_b128 v[2:5], v0
	ds_read_b128 v[6:9], v0 offset:8704
	ds_read_b128 v[10:13], v0 offset:32
	ds_read_b128 v[168:171], v0 offset:8736
	ds_read_b128 v[172:175], v0 offset:64
	ds_read_b128 v[176:179], v0 offset:8768
	ds_read_b128 v[180:183], v0 offset:96
	ds_read_b128 v[184:187], v0 offset:8800
	ds_read_b128 v[188:191], v0 offset:128
	ds_read_b128 v[192:195], v0 offset:8832
	ds_read_b128 v[204:207], v0 offset:160
	ds_read_b128 v[208:211], v0 offset:8864
	ds_read_b128 v[212:215], v0 offset:192
	ds_read_b128 v[216:219], v0 offset:8896
	ds_read_b128 v[220:223], v0 offset:224
	s_waitcnt lgkmcnt(14)
	v_mfma_f32_32x32x16_bf16 v[96:111], v[2:5], v[140:143], 0
	ds_read_b128 v[224:227], v0 offset:8928
	s_waitcnt lgkmcnt(14)
	v_mfma_f32_32x32x16_bf16 v[80:95], v[6:9], v[140:143], 0
	s_waitcnt lgkmcnt(13)
	v_mfma_f32_32x32x16_bf16 v[96:111], v[10:13], v[136:139], v[96:111]
	s_waitcnt lgkmcnt(12)
	v_mfma_f32_32x32x16_bf16 v[80:95], v[168:171], v[136:139], v[80:95]
	s_waitcnt lgkmcnt(11)
	v_mfma_f32_32x32x16_bf16 v[96:111], v[172:175], v[132:135], v[96:111]
	s_waitcnt lgkmcnt(10)
	v_mfma_f32_32x32x16_bf16 v[80:95], v[176:179], v[132:135], v[80:95]
	s_waitcnt lgkmcnt(9)
	v_mfma_f32_32x32x16_bf16 v[96:111], v[180:183], v[128:131], v[96:111]
	s_waitcnt lgkmcnt(8)
	v_mfma_f32_32x32x16_bf16 v[80:95], v[184:187], v[128:131], v[80:95]
	s_waitcnt lgkmcnt(7)
	v_mfma_f32_32x32x16_bf16 v[96:111], v[188:191], v[124:127], v[96:111]
	s_waitcnt lgkmcnt(6)
	v_mfma_f32_32x32x16_bf16 v[80:95], v[192:195], v[124:127], v[80:95]
	s_waitcnt lgkmcnt(5)
	v_mfma_f32_32x32x16_bf16 v[96:111], v[204:207], v[120:123], v[96:111]
	s_waitcnt lgkmcnt(4)
	v_mfma_f32_32x32x16_bf16 v[80:95], v[208:211], v[120:123], v[80:95]
	s_waitcnt lgkmcnt(3)
	v_mfma_f32_32x32x16_bf16 v[96:111], v[212:215], v[116:119], v[96:111]
	s_waitcnt lgkmcnt(2)
	v_mfma_f32_32x32x16_bf16 v[80:95], v[216:219], v[116:119], v[80:95]
	s_waitcnt lgkmcnt(1)
	v_mfma_f32_32x32x16_bf16 v[96:111], v[220:223], v[112:115], v[96:111]
	s_waitcnt lgkmcnt(0)
	v_mfma_f32_32x32x16_bf16 v[80:95], v[224:227], v[112:115], v[80:95]
	s_setprio 0
	s_nop 10
	v_max_f32_e32 v0, v81, v81
	v_max_f32_e32 v2, v97, v97
	v_max_f32_e32 v0, v2, v0
	v_max_f32_e32 v2, v82, v82
	v_max_f32_e32 v3, v98, v98
	v_max_f32_e32 v2, v3, v2
	v_max_f32_e32 v3, v83, v83
	v_max_f32_e32 v4, v99, v99
	v_max3_f32 v0, v96, v80, v0
	v_max_f32_e32 v3, v4, v3
	v_max3_f32 v0, v0, v2, v3
	v_max_f32_e32 v2, v84, v84
	v_max_f32_e32 v3, v100, v100
	v_max_f32_e32 v2, v3, v2
	v_max_f32_e32 v3, v85, v85
	v_max_f32_e32 v4, v101, v101
	v_max_f32_e32 v3, v4, v3
	v_max3_f32 v0, v0, v2, v3
	v_max_f32_e32 v2, v86, v86
	v_max_f32_e32 v3, v102, v102
	v_max_f32_e32 v2, v3, v2
	v_max_f32_e32 v3, v87, v87
	v_max_f32_e32 v4, v103, v103
	v_max_f32_e32 v3, v4, v3
	v_max3_f32 v0, v0, v2, v3
	v_max_f32_e32 v2, v88, v88
	v_max_f32_e32 v3, v104, v104
	v_max_f32_e32 v2, v3, v2
	v_max_f32_e32 v3, v89, v89
	v_max_f32_e32 v4, v105, v105
	v_max_f32_e32 v3, v4, v3
	v_max3_f32 v0, v0, v2, v3
	v_max_f32_e32 v2, v90, v90
	v_max_f32_e32 v3, v106, v106
	v_max_f32_e32 v2, v3, v2
	v_max_f32_e32 v3, v91, v91
	v_max_f32_e32 v4, v107, v107
	v_max_f32_e32 v3, v4, v3
	v_max3_f32 v0, v0, v2, v3
	v_max_f32_e32 v2, v92, v92
	v_max_f32_e32 v3, v108, v108
	v_max_f32_e32 v2, v3, v2
	v_max_f32_e32 v3, v93, v93
	v_max_f32_e32 v4, v109, v109
	v_max_f32_e32 v3, v4, v3
	v_max3_f32 v0, v0, v2, v3
	v_max_f32_e32 v2, v94, v94
	v_max_f32_e32 v3, v110, v110
	v_max_f32_e32 v2, v3, v2
	v_max_f32_e32 v3, v95, v95
	v_max_f32_e32 v4, v111, v111
	v_max_f32_e32 v3, v4, v3
	v_max3_f32 v0, v0, v2, v3
	v_mov_b32_e32 v2, v0
	s_nop 1
	v_permlane32_swap_b32_e32 v0, v2
	v_max3_f32 v0, v153, v0, v2
	v_sub_f32_e32 v2, v153, v0
	v_exp_f32_e32 v2, v2
	v_cmp_gt_f32_e32 vcc, v0, v153
	s_cbranch_vccz .LBB0_530
	v_pk_mul_f32 v[78:79], v[78:79], v[2:3] op_sel_hi:[1,0]
	v_pk_mul_f32 v[76:77], v[76:77], v[2:3] op_sel_hi:[1,0]
	v_pk_mul_f32 v[74:75], v[74:75], v[2:3] op_sel_hi:[1,0]
	v_pk_mul_f32 v[72:73], v[72:73], v[2:3] op_sel_hi:[1,0]
	v_pk_mul_f32 v[70:71], v[70:71], v[2:3] op_sel_hi:[1,0]
	v_pk_mul_f32 v[68:69], v[68:69], v[2:3] op_sel_hi:[1,0]
	v_pk_mul_f32 v[66:67], v[66:67], v[2:3] op_sel_hi:[1,0]
	v_pk_mul_f32 v[64:65], v[64:65], v[2:3] op_sel_hi:[1,0]
	v_pk_mul_f32 v[62:63], v[62:63], v[2:3] op_sel_hi:[1,0]
	v_pk_mul_f32 v[60:61], v[60:61], v[2:3] op_sel_hi:[1,0]
	v_pk_mul_f32 v[58:59], v[58:59], v[2:3] op_sel_hi:[1,0]
	v_pk_mul_f32 v[56:57], v[56:57], v[2:3] op_sel_hi:[1,0]
	v_pk_mul_f32 v[54:55], v[54:55], v[2:3] op_sel_hi:[1,0]
	v_pk_mul_f32 v[52:53], v[52:53], v[2:3] op_sel_hi:[1,0]
	v_pk_mul_f32 v[50:51], v[50:51], v[2:3] op_sel_hi:[1,0]
	v_pk_mul_f32 v[48:49], v[48:49], v[2:3] op_sel_hi:[1,0]
	v_pk_mul_f32 v[46:47], v[46:47], v[2:3] op_sel_hi:[1,0]
	v_pk_mul_f32 v[44:45], v[44:45], v[2:3] op_sel_hi:[1,0]
	v_pk_mul_f32 v[42:43], v[42:43], v[2:3] op_sel_hi:[1,0]
	v_pk_mul_f32 v[40:41], v[40:41], v[2:3] op_sel_hi:[1,0]
	v_pk_mul_f32 v[38:39], v[38:39], v[2:3] op_sel_hi:[1,0]
	v_pk_mul_f32 v[36:37], v[36:37], v[2:3] op_sel_hi:[1,0]
	v_pk_mul_f32 v[34:35], v[34:35], v[2:3] op_sel_hi:[1,0]
	v_pk_mul_f32 v[32:33], v[32:33], v[2:3] op_sel_hi:[1,0]
	v_pk_mul_f32 v[30:31], v[30:31], v[2:3] op_sel_hi:[1,0]
	v_pk_mul_f32 v[28:29], v[28:29], v[2:3] op_sel_hi:[1,0]
	v_pk_mul_f32 v[26:27], v[26:27], v[2:3] op_sel_hi:[1,0]
	v_pk_mul_f32 v[24:25], v[24:25], v[2:3] op_sel_hi:[1,0]
	v_pk_mul_f32 v[22:23], v[22:23], v[2:3] op_sel_hi:[1,0]
	v_pk_mul_f32 v[20:21], v[20:21], v[2:3] op_sel_hi:[1,0]
	v_pk_mul_f32 v[18:19], v[18:19], v[2:3] op_sel_hi:[1,0]
	v_pk_mul_f32 v[16:17], v[16:17], v[2:3] op_sel_hi:[1,0]
	s_branch .LBB0_530
